# mixer phase: one static s_setprio 1 for waves 4-7 (the waves with the long causal strips) at phase entry
# speedup vs baseline: 1.0144x; 1.0072x over previous
; #define LAS __attribute__((address_space(3)))
;     DI unsigned* fCTL() const { return (unsigned*)(ws + WS_CTL); }
; DI void phase_mixers(const Params& p, const Ctx& c, int l, int g) {
;     const int Bg = g ? 8 : 16, S = g ? 4096 : 2048, nqb = S / 128;
;     const int nml = 2 * Bg * 8, nssd = 2 * Bg * 8, natt = Bg * nqb * 2, total = nml + nssd + natt;
;     LAS int* sitem = (LAS int*)(c.lds + LDS_MAIN);
;     unsigned* ctr = c.fCTL() + l * 2 + g;
;     for (;;) {
;         if (threadIdx.x == 0) sitem[0] = (int)atomicAdd(ctr, 1u);
;         __syncthreads();
.LBB0_288:
	s_or_b64 exec, exec, s[36:37]
	s_and_b64 s[20:21], s[44:45], exec
	s_movk_i32 s2, 0x80
	s_cselect_b32 s2, 0x100, s2
	s_lshr_b32 s34, s30, 7
	s_and_b64 s[20:21], s[44:45], exec
	v_writelane_b32 v253, s2, 59
	s_cselect_b32 s2, 4, 3
	s_lshl_b32 s2, s34, s2
	s_lshl_b32 s35, s2, 1
	s_and_b64 s[20:21], s[44:45], exec
	s_movk_i32 s2, 0x100
	v_cvt_f32_ubyte0_e32 v1, s34
	s_cselect_b32 s2, 0x200, s2
	v_rcp_iflag_f32_e32 v1, v1
	v_writelane_b32 v255, s2, 6
	s_add_i32 s35, s35, s2
	s_lshl_b64 s[20:21], s[74:75], 2
	v_readlane_b32 s2, v254, 50
	s_add_u32 s20, s2, s20
	v_readlane_b32 s2, v254, 51
	s_addc_u32 s21, s2, s21
	v_writelane_b32 v255, s20, 7
	s_add_i32 s95, s30, 0xffffff00
	v_mul_f32_e32 v1, 0x4f7ffffe, v1
	v_writelane_b32 v255, s21, 8
	s_and_b64 s[20:21], s[44:45], exec
	s_movk_i32 s2, 0xfe00
	v_cvt_u32_f32_e32 v1, v1
	s_cselect_b32 s2, s2, 0xffffff00
	v_writelane_b32 v255, s2, 9
	s_cselect_b32 s2, 11, 12
	v_writelane_b32 v255, s2, 10
	s_add_i32 s2, s30, 0xffffff80
	v_writelane_b32 v255, s2, 11
	s_sub_i32 s2, 0, s34
	v_readfirstlane_b32 s20, v1
	s_mul_i32 s2, s2, s20
	s_mul_hi_u32 s2, s20, s2
	s_add_i32 s2, s20, s2
	v_writelane_b32 v255, s2, 12
	s_and_b32 s2, s30, 0x1f80
	v_writelane_b32 v255, s2, 13
	s_waitcnt lgkmcnt(0)
	s_barrier
	v_readfirstlane_b32 s2, v167
	s_nop 3
	s_cmpk_lt_u32 s2, 0x100
	s_cbranch_scc1 .Lmix_prio_skip
	s_setprio 1
.Lmix_prio_skip:
	s_branch .LBB0_292
